# combine and convfix loops: independent loads issued together (one round trip per iteration instead of 2-4), no wait on previous store
# speedup vs baseline: 1.1280x; 1.0057x over previous
.LBB0_71:
	s_or_b64 exec, exec, s[12:13]
	v_ashrrev_i32_e32 v5, 31, v4
	v_lshlrev_b64 v[8:9], 2, v[4:5]
	v_lshl_add_u64 v[12:13], s[6:7], 0, v[8:9]
	v_add_co_u32_e32 v22, vcc, 0x5000, v12
	global_load_dword v14, v[12:13], off
	s_nop 0
	v_addc_co_u32_e32 v23, vcc, 0, v13, vcc
	global_load_dword v21, v[22:23], off offset:2048
	v_add_co_u32_e32 v22, vcc, 0xb000, v12
	v_add_u32_e32 v2, 0xb00, v4
	s_nop 0
	v_addc_co_u32_e32 v23, vcc, 0, v13, vcc
	global_load_dword v15, v[22:23], off
	v_lshl_add_u64 v[24:25], s[8:9], 0, v[8:9]
	global_load_dword v30, v[24:25], off
	v_lshlrev_b64 v[24:25], 2, v[2:3]
	v_lshl_add_u64 v[26:27], s[6:7], 0, v[24:25]
	global_load_dword v31, v[26:27], off
	s_mov_b32 s2, 0x8000
	s_nop 0
	v_add_co_u32_e32 v26, vcc, s2, v12
	s_mov_b32 s2, 0xd000
	s_nop 0
	v_addc_co_u32_e32 v27, vcc, 0, v13, vcc
	v_add_co_u32_e32 v28, vcc, s2, v12
	global_load_dword v32, v[26:27], off offset:1024
	s_nop 0
	v_addc_co_u32_e32 v29, vcc, 0, v13, vcc
	global_load_dword v33, v[28:29], off offset:3072
	v_lshl_add_u64 v[24:25], s[8:9], 0, v[24:25]
	global_load_dword v34, v[24:25], off
	v_add_u32_e32 v16, s0, v16
	v_add_u32_e32 v17, s16, v17
	s_waitcnt vmcnt(0)
	v_pk_mul_f32 v[6:7], v[6:7], v[14:15]
	s_nop 0
	v_fma_f32 v6, v20, v21, v6
	v_add_f32_e32 v14, v6, v7
	v_add_f32_e32 v14, v30, v14
	v_pk_mul_f32 v[8:9], v[10:11], v[32:33]
	s_nop 0
	v_fma_f32 v2, v19, v31, v8
	v_add_f32_e32 v2, v2, v9
	v_add_f32_e32 v2, v34, v2
	v_mul_f32_e32 v6, 0xbfb8aa3b, v14
	v_exp_f32_e32 v6, v6
	s_nop 0
	v_add_f32_e32 v6, 1.0, v6
	v_div_scale_f32 v7, s[2:3], v6, v6, v14
	v_rcp_f32_e32 v8, v7
	v_readlane_b32 s2, v251, 12
	v_readlane_b32 s3, v251, 13
	v_fma_f32 v9, -v7, v8, 1.0
	v_fmac_f32_e32 v8, v9, v8
	v_div_scale_f32 v9, vcc, v14, v6, v14
	v_mul_f32_e32 v10, v9, v8
	v_fma_f32 v11, -v7, v10, v9
	v_fmac_f32_e32 v10, v11, v8
	v_fma_f32 v7, -v7, v10, v9
	v_div_fmas_f32 v7, v7, v8, v10
	v_div_fixup_f32 v6, v7, v6, v14
	v_mul_f32_e32 v2, v6, v2
	v_mov_b64_e32 v[6:7], s[2:3]
	s_movk_i32 s2, 0x1600
	v_mad_i64_i32 v[6:7], s[2:3], v18, s2, v[6:7]
	s_mov_b32 s2, 0x57fff
	s_nop 0
	v_cmp_lt_i32_e32 vcc, s2, v16
	v_cvt_pk_bf16_f32 v2, v2, s0
	v_lshl_add_u64 v[4:5], v[4:5], 1, v[6:7]
	s_or_b64 s[10:11], vcc, s[10:11]
	global_store_short v[4:5], v2, off
	s_andn2_b64 exec, exec, s[10:11]
	s_cbranch_execz .LBB0_85

.LBB0_304:
	v_ashrrev_i32_e32 v6, 12, v4
	v_add_u32_e32 v7, 0x80, v6
	v_mul_hi_i32 v8, v7, s16
	v_lshrrev_b32_e32 v9, 31, v8
	v_ashrrev_i32_e32 v8, 4, v8
	v_add_u32_e32 v8, v8, v9
	v_mul_lo_u32 v9, v8, s17
	v_sub_u32_e32 v19, v7, v9
	v_ashrrev_i32_e32 v9, 31, v8
	v_lshlrev_b32_e32 v7, 8, v19
	v_bfe_u32 v2, v4, 4, 8
	v_lshlrev_b64 v[8:9], 12, v[8:9]
	v_and_b32_e32 v7, 0xf00, v7
	v_or3_b32 v8, v8, v7, v2
	v_ashrrev_i32_e32 v7, 31, v6
	v_lshlrev_b64 v[6:7], 8, v[6:7]
	v_or_b32_e32 v6, v6, v2
	v_lshl_add_u64 v[10:11], v[6:7], 0, s[10:11]
	v_lshlrev_b64 v[14:15], 11, v[8:9]
	v_lshl_add_u64 v[8:9], v[6:7], 3, s[14:15]
	v_lshl_add_u64 v[12:13], v[10:11], 3, s[14:15]
	global_load_dwordx2 v[8:9], v[8:9], off
	v_and_b32_e32 v18, 60, v5
	global_load_dwordx2 v[12:13], v[12:13], off
	v_lshlrev_b64 v[6:7], 8, v[6:7]
	v_lshlrev_b64 v[10:11], 8, v[10:11]
	v_lshl_add_u64 v[6:7], s[12:13], 0, v[6:7]
	v_lshl_add_u64 v[10:11], s[12:13], 0, v[10:11]
	v_add_u32_e32 v4, s0, v4
	s_mov_b32 s7, 0x3ffff
	v_add_u32_e32 v5, s6, v5
	v_lshlrev_b32_e32 v20, 2, v18
	v_mov_b32_e32 v21, 0
	v_lshl_add_u64 v[6:7], v[6:7], 0, v[20:21]
	v_lshl_add_u64 v[10:11], v[10:11], 0, v[20:21]
	global_load_dwordx4 v[22:25], v[6:7], off
	global_load_dwordx4 v[26:29], v[10:11], off
	s_waitcnt vmcnt(3)
	v_max_f32_e32 v2, v8, v8
	s_waitcnt vmcnt(2)
	v_max_f32_e32 v16, v12, v12
	v_max_f32_e32 v2, v2, v16
	v_sub_f32_e32 v8, v8, v2
	v_sub_f32_e32 v2, v12, v2
	v_exp_f32_e32 v16, v8
	v_exp_f32_e32 v17, v2
	v_mov_b32_e32 v12, v9
	v_pk_mul_f32 v[8:9], v[12:13], v[16:17]
	s_nop 0
	v_add_f32_e32 v2, v8, v9
	v_div_scale_f32 v12, s[8:9], v2, v2, 1.0
	v_rcp_f32_e32 v13, v12
	s_nop 0
	v_fma_f32 v16, -v12, v13, 1.0
	v_fmac_f32_e32 v13, v16, v13
	v_div_scale_f32 v16, vcc, 1.0, v2, 1.0
	v_mul_f32_e32 v17, v16, v13
	v_fma_f32 v20, -v12, v17, v16
	v_fmac_f32_e32 v17, v20, v13
	v_fma_f32 v12, -v12, v17, v16
	v_div_fmas_f32 v12, v12, v13, v17
	v_div_fixup_f32 v12, v12, v2, 1.0
	v_mul_f32_e32 v2, v8, v12
	v_mul_f32_e32 v16, v9, v12
	s_waitcnt vmcnt(0)
	v_pk_mul_f32 v[10:11], v[26:27], v[16:17] op_sel_hi:[1,0]
	s_nop 0
	v_pk_fma_f32 v[6:7], v[22:23], v[2:3], v[10:11] op_sel_hi:[1,0,1]
	v_pk_mul_f32 v[10:11], v[16:17], v[28:29] op_sel_hi:[0,1]
	v_pk_fma_f32 v[8:9], v[24:25], v[2:3], v[10:11] op_sel_hi:[1,0,1]
	v_lshlrev_b32_e32 v2, 2, v19
	v_and_b32_e32 v10, 0xffffffc0, v2
	v_cvt_pk_bf16_f32 v6, v6, v7
	v_cvt_pk_bf16_f32 v7, v8, v9
	v_lshl_add_u64 v[8:9], s[88:89], 0, v[14:15]
	v_ashrrev_i32_e32 v11, 31, v10
	v_lshl_add_u64 v[8:9], v[10:11], 1, v[8:9]
	v_lshlrev_b32_e32 v2, 1, v18
	v_lshl_add_u64 v[8:9], v[8:9], 0, v[2:3]
	v_add_co_u32_e32 v8, vcc, 0x11340000, v8
	s_nop 1
	v_addc_co_u32_e32 v9, vcc, 0, v9, vcc
	v_cmp_lt_i32_e32 vcc, s7, v4
	s_or_b64 s[4:5], vcc, s[4:5]
	global_store_dwordx2 v[8:9], v[6:7], off offset:1280
	s_andn2_b64 exec, exec, s[4:5]
	s_cbranch_execnz .LBB0_304
